# v111 plus two chunk-prep changes that only show under 3x amplification (-2.4 us per pass): step-2 row scalars read once, next unit's step-1 operands requested during step 4
# speedup vs baseline: 1.0023x; 1.0003x over previous
; #define PG8_LAS __attribute__((address_space(3)))
; __device__ __forceinline__ void phase_prep(const Args& a, PG8_LAS unsigned char* lds) {
;     const int tid = threadIdx.x, lane = tid & 63, wave = __builtin_amdgcn_readfirstlane(tid >> 6), half = wave >> 2, lw = wave & 3, q = lane >> 4, r = lane & 15;
;     const int role = (lw - half) & 3;
;     PG8_LAS unsigned char* hb = lds + half * 36864;
;     PG8_LAS float* sG = (PG8_LAS float*)hb; PG8_LAS float* sB = sG + 64; PG8_LAS float* sE = sG + 128; PG8_LAS float* sK = sG + 192; PG8_LAS float* sL = sG + 256;
;     PG8_LAS unsigned char* Tu = hb + 17408; PG8_LAS unsigned char* Tw = Tu + 9216;
;     const bf16_t* qb = (const bf16_t*)(a.ws + WS_QB); const bf16_t* kb = (const bf16_t*)(a.ws + WS_KB);
;     const bf16_t* kT = (const bf16_t*)(a.ws + WS_KT); const bf16_t* vT = (const bf16_t*)(a.ws + WS_VT);
;     const float* betaB = (const float*)(a.ws + WS_BETA); const float* gB = (const float*)(a.ws + WS_G); float* glast = (float*)(a.ws + WS_GL);
;     for (int unit = blockIdx.x; unit < 1024; unit += gridDim.x) {
;         const int hp = unit & 1, bn = unit >> 1, h = 2 * hp + half, item = bn * 4 + h; const size_t r0 = (size_t)bn * 64;
;         unsigned char* pi = a.ws + WS_PREP + (size_t)item * PREP_ITEM;
;         bf16_t* wp = (bf16_t*)(pi + PI_W); bf16_t* qgp = (bf16_t*)(pi + PI_QG); bf16_t* kdTp = (bf16_t*)(pi + PI_KD); bf16_t* uT = (bf16_t*)(pi + PI_UT); bf16_t* aqkp = (bf16_t*)(pi + PI_AQ);
;         const bf16_t* qbase = qb + r0 * 512 + h * 128; const bf16_t* kbase = kb + r0 * 512 + h * 128;
;         const bf16_t* kTb = kT + ((size_t)bn * 512 + h * 128) * 64; const bf16_t* vTb = vT + ((size_t)bn * 512 + h * 128) * 64;
;         bf16x8 ak[4], aq[4], bkf[2][4];
; #pragma unroll
;         for (int s = 0; s < 4; ++s) { ak[s] = *(const bf16x8*)(kbase + (size_t)(16 * lw + r) * 512 + 32 * s + 8 * q); aq[s] = *(const bf16x8*)(qbase + (size_t)(16 * lw + r) * 512 + 32 * s + 8 * q); }
; #pragma unroll
;         for (int tj = 0; tj < 2; ++tj)
; #pragma unroll
;             for (int s = 0; s < 4; ++s) bkf[tj][s] = *(const bf16x8*)(kbase + (size_t)(16 * tj + r) * 512 + 32 * s + 8 * q);
;         bf16x8 pv[2][2], pk[2][2];
;         if (role != 0) {
; #pragma unroll
;         for (int cc = 0; cc < 2; ++cc) { const int ct = 2 * lw + cc;
.LBB0_249:
	s_or_b64 exec, exec, s[0:1]
	s_add_u32 s10, s16, 0x2000000
	s_addc_u32 s11, s17, 0
	v_readlane_b32 s0, v253, 17
	s_bitcmp0_b32 s0, 3
	s_waitcnt lgkmcnt(0)
	s_barrier
	s_cbranch_scc1 .LBB0_301
	s_cmpk_gt_i32 s82, 0x3ff
	v_readfirstlane_b32 s0, v152
	v_and_b32_e32 v254, 63, v152
	v_lshlrev_b32_e32 v254, 4, v254
	v_lshrrev_b32_e32 v255, 8, v152
	v_mul_u32_u24_e32 v255, 0x6200, v255
	v_add_u32_e32 v254, v254, v255
	v_add_u32_e32 v254, 0x1a000, v254
	v_bfe_u32 v255, v152, 6, 2
	v_lshl_add_u32 v255, v255, 12, v254
	s_mov_b32 s99, 0
	s_cbranch_scc1 .LBB0_301
	v_mbcnt_lo_u32_b32 v0, -1, 0
	s_waitcnt vmcnt(14)
	v_mbcnt_hi_u32_b32 v7, -1, v0
	s_waitcnt vmcnt(12)
	v_and_b32_e32 v9, 64, v7
	s_waitcnt vmcnt(7)
	v_add_u32_e32 v16, -1, v7
	v_cmp_lt_i32_e32 vcc, v16, v9
	v_and_b32_e32 v1, 63, v152
	v_bfrev_b32_e32 v0, 0.5
	v_cndmask_b32_e32 v16, v16, v7, vcc
	v_lshlrev_b32_e32 v131, 2, v16
	v_add_u32_e32 v16, -2, v7
	v_cmp_lt_i32_e32 vcc, v16, v9
	v_lshl_or_b32 v99, v7, 2, v0
	s_lshr_b32 s1, s0, 6
	v_cndmask_b32_e32 v16, v16, v7, vcc
	v_lshlrev_b32_e32 v132, 2, v16
	v_add_u32_e32 v16, -4, v7
	v_cmp_lt_i32_e32 vcc, v16, v9
	s_lshr_b32 s33, s0, 8
	v_writelane_b32 v253, s76, 39
	v_cndmask_b32_e32 v16, v16, v7, vcc
	v_lshlrev_b32_e32 v133, 2, v16
	v_add_u32_e32 v16, -8, v7
	v_cmp_lt_i32_e32 vcc, v16, v9
	s_sub_i32 s1, s1, s33
	v_writelane_b32 v253, s77, 40
	v_cndmask_b32_e32 v16, v16, v7, vcc
	v_lshlrev_b32_e32 v134, 2, v16
	v_add_u32_e32 v16, -16, v7
	v_cmp_lt_i32_e32 vcc, v16, v9
	s_and_b32 s28, s1, 3
	s_mul_i32 s1, s33, 0x9000
	v_cndmask_b32_e32 v16, v16, v7, vcc
	v_lshlrev_b32_e32 v135, 2, v16
	v_subrev_u32_e32 v16, 32, v7
	v_cmp_lt_i32_e32 vcc, v16, v9
	v_writelane_b32 v253, s78, 41
	s_add_i32 s4, s1, 0
	v_cndmask_b32_e32 v7, v16, v7, vcc
	v_cmp_eq_u32_e32 vcc, 1, v1
	v_writelane_b32 v253, s79, 42
	s_add_u32 s1, s16, 0x10000000
	v_cndmask_b32_e64 v140, 0, 1.0, vcc
	v_cmp_eq_u32_e32 vcc, 2, v1
	v_writelane_b32 v253, s1, 43
	s_addc_u32 s1, s17, 0
	v_cndmask_b32_e64 v141, 0, 1.0, vcc
	v_cmp_eq_u32_e32 vcc, 3, v1
	v_writelane_b32 v253, s1, 44
	s_add_u32 s1, s16, 0x12000000
	v_cndmask_b32_e64 v142, 0, 1.0, vcc
	v_cmp_eq_u32_e32 vcc, 4, v1
	v_writelane_b32 v253, s1, 45
	s_addc_u32 s1, s17, 0
	v_cndmask_b32_e64 v143, 0, 1.0, vcc
	v_cmp_eq_u32_e32 vcc, 5, v1
	v_writelane_b32 v253, s1, 46
	s_add_u32 s1, s16, 0x4000000
	v_cndmask_b32_e64 v144, 0, 1.0, vcc
	v_cmp_eq_u32_e32 vcc, 6, v1
	v_writelane_b32 v253, s1, 47
	s_addc_u32 s1, s17, 0
	v_cndmask_b32_e64 v145, 0, 1.0, vcc
	v_cmp_eq_u32_e32 vcc, 7, v1
	s_add_u32 s6, s16, 0x1800000
	s_addc_u32 s7, s17, 0
	v_cndmask_b32_e64 v146, 0, 1.0, vcc
	v_cmp_eq_u32_e32 vcc, 8, v1
	v_writelane_b32 v253, s1, 48
	s_add_u32 s8, s16, 0x1880000
	v_cndmask_b32_e64 v147, 0, 1.0, vcc
	v_cmp_eq_u32_e32 vcc, 9, v1
	v_writelane_b32 v253, s6, 49
	s_addc_u32 s9, s17, 0
	v_cndmask_b32_e64 v148, 0, 1.0, vcc
	v_cmp_eq_u32_e32 vcc, 10, v1
	v_writelane_b32 v253, s7, 50
	s_add_u32 s1, s16, 0x1b00000
	v_cndmask_b32_e64 v149, 0, 1.0, vcc
	v_cmp_eq_u32_e32 vcc, 11, v1
	v_writelane_b32 v253, s1, 51
	s_addc_u32 s1, s17, 0
	v_cndmask_b32_e64 v150, 0, 1.0, vcc
	v_cmp_eq_u32_e32 vcc, 12, v1
	s_bfe_u32 s0, s0, 0x20006
	s_cmp_lg_u32 s28, 0
	v_cndmask_b32_e64 v151, 0, 1.0, vcc
	v_cmp_eq_u32_e32 vcc, 13, v1
	v_writelane_b32 v253, s1, 52
	s_cselect_b64 s[6:7], -1, 0
	v_cndmask_b32_e64 v154, 0, 1.0, vcc
	v_cmp_eq_u32_e32 vcc, 14, v1
	v_writelane_b32 v253, s6, 53
	s_cmp_eq_u32 s0, 0
	v_cndmask_b32_e64 v155, 0, 1.0, vcc
	v_cmp_eq_u32_e32 vcc, 15, v1
	v_writelane_b32 v253, s7, 54
	s_cselect_b64 s[6:7], -1, 0
	v_cndmask_b32_e64 v156, 0, 1.0, vcc
	v_cmp_eq_u32_e32 vcc, 16, v1
	v_mov_b32_e32 v97, 0
	v_writelane_b32 v253, s6, 55
	v_cndmask_b32_e64 v157, 0, 1.0, vcc
	v_cmp_eq_u32_e32 vcc, 17, v1
	v_and_b32_e32 v3, 15, v152
	v_bfe_u32 v5, v152, 4, 2
	v_cndmask_b32_e64 v158, 0, 1.0, vcc
	v_cmp_eq_u32_e32 vcc, 18, v1
	v_writelane_b32 v253, s7, 56
	v_cmp_eq_u32_sdwa s[6:7], v152, v97 src0_sel:BYTE_0 src1_sel:DWORD
	v_cndmask_b32_e64 v159, 0, 1.0, vcc
	v_cmp_eq_u32_e32 vcc, 19, v1
	v_lshlrev_b32_e32 v11, 1, v152
	v_and_b32_e32 v0, 3, v152
	v_cndmask_b32_e64 v160, 0, 1.0, vcc
	v_cmp_eq_u32_e32 vcc, 20, v1
	s_lshl_b32 s1, s0, 6
	v_lshlrev_b32_e32 v6, 9, v3
	v_cndmask_b32_e64 v161, 0, 1.0, vcc
	v_cmp_eq_u32_e32 vcc, 21, v1
	v_lshlrev_b32_e32 v12, 3, v5
	v_writelane_b32 v253, s6, 57
	v_cndmask_b32_e64 v162, 0, 1.0, vcc
	v_cmp_eq_u32_e32 vcc, 22, v1
	v_and_or_b32 v13, v11, 24, v0
	v_lshlrev_b32_e32 v0, 2, v5
	v_cndmask_b32_e64 v163, 0, 1.0, vcc
	v_cmp_eq_u32_e32 vcc, 23, v1
	s_add_i32 s1, s4, s1
	v_and_b32_e32 v2, 48, v152
	v_cndmask_b32_e64 v164, 0, 1.0, vcc
	v_cmp_eq_u32_e32 vcc, 24, v1
	v_lshl_or_b32 v4, s28, 6, v1
	v_lshlrev_b32_e32 v10, 6, v3
	v_cndmask_b32_e64 v165, 0, 1.0, vcc
	v_cmp_eq_u32_e32 vcc, 25, v1
	v_lshl_or_b32 v8, s0, 13, v6
	v_writelane_b32 v253, s7, 58
	v_cndmask_b32_e64 v166, 0, 1.0, vcc
	v_cmp_eq_u32_e32 vcc, 26, v1
	v_lshl_or_b32 v33, s0, 4, v0
	v_add_u32_e32 v15, s1, v2
	v_add_u32_e32 v96, 0xffffff80, v4
	v_lshl_or_b32 v4, s0, 5, v12
	v_lshl_or_b32 v10, s0, 11, v10
	v_cmp_gt_u32_e64 s[0:1], 2, v1
	v_cndmask_b32_e64 v167, 0, 1.0, vcc
	v_cmp_eq_u32_e32 vcc, 27, v1
	v_writelane_b32 v253, s0, 59
	v_or_b32_e32 v35, 1, v33
	v_cndmask_b32_e64 v168, 0, 1.0, vcc
	v_cmp_eq_u32_e32 vcc, 28, v1
	v_writelane_b32 v253, s1, 60
	v_cmp_gt_u32_e64 s[0:1], 4, v1
	v_cndmask_b32_e64 v169, 0, 1.0, vcc
	v_cmp_eq_u32_e32 vcc, 29, v1
	v_writelane_b32 v253, s0, 61
	v_or_b32_e32 v37, 2, v33
	v_cndmask_b32_e64 v170, 0, 1.0, vcc
	v_cmp_eq_u32_e32 vcc, 30, v1
	v_writelane_b32 v253, s1, 62
	v_cmp_gt_u32_e64 s[0:1], 8, v1
	v_cndmask_b32_e64 v171, 0, 1.0, vcc
	v_cmp_eq_u32_e32 vcc, 31, v1
	v_writelane_b32 v253, s0, 63
	v_or_b32_e32 v39, 3, v33
	v_cndmask_b32_e64 v172, 0, 1.0, vcc
	v_cmp_eq_u32_e32 vcc, 32, v1
	v_writelane_b32 v252, s1, 0
	v_cmp_gt_u32_e64 s[0:1], 16, v1
	v_cndmask_b32_e64 v173, 0, 1.0, vcc
	v_cmp_eq_u32_e32 vcc, 33, v1
	v_writelane_b32 v252, s0, 1
	v_or_b32_e32 v25, 16, v3
	v_cndmask_b32_e64 v174, 0, 1.0, vcc
	v_cmp_eq_u32_e32 vcc, 34, v1
	v_writelane_b32 v252, s1, 2
	v_cmp_gt_u32_e64 s[0:1], 32, v1
	v_cndmask_b32_e64 v175, 0, 1.0, vcc
	v_cmp_eq_u32_e32 vcc, 35, v1
	v_writelane_b32 v252, s0, 3
	v_lshlrev_b32_e32 v136, 2, v7
	v_cndmask_b32_e64 v176, 0, 1.0, vcc
	v_cmp_eq_u32_e32 vcc, 36, v1
	v_writelane_b32 v252, s1, 4
	v_cmp_ge_u32_e64 s[0:1], v33, v3
	v_cndmask_b32_e64 v177, 0, 1.0, vcc
	v_cmp_eq_u32_e32 vcc, 37, v1
	v_writelane_b32 v252, s0, 5
	v_lshlrev_b32_e32 v7, 6, v33
	v_cndmask_b32_e64 v178, 0, 1.0, vcc
	v_cmp_eq_u32_e32 vcc, 38, v1
	v_writelane_b32 v252, s1, 6
	v_cmp_gt_u32_e64 s[0:1], v33, v3
	v_cndmask_b32_e64 v179, 0, 1.0, vcc
	v_cmp_eq_u32_e32 vcc, 39, v1
	v_writelane_b32 v252, s0, 7
	v_lshlrev_b32_e32 v9, 6, v35
	v_cndmask_b32_e64 v180, 0, 1.0, vcc
	v_cmp_eq_u32_e32 vcc, 40, v1
	v_writelane_b32 v252, s1, 8
	v_cmp_lt_u32_e64 s[0:1], v35, v3
	v_cndmask_b32_e64 v181, 0, 1.0, vcc
	v_cmp_eq_u32_e32 vcc, 41, v1
	v_writelane_b32 v252, s0, 9
	s_waitcnt vmcnt(4)
; __device__ __forceinline__ void phase_prep(const Args& a, PG8_LAS unsigned char* lds) {
;     ...
;             for (int tj = 0; tj < 4; ++tj) {
;                 f32x4 ckk = {0.f, 0.f, 0.f, 0.f}, cqk = {0.f, 0.f, 0.f, 0.f};
; #pragma unroll
;                 for (int s = 0; s < 4; ++s) { const bf16x8 bk = (tj < 2) ? bkf[tj & 1][s] : *(const bf16x8*)(kbase + (size_t)(16 * tj + r) * 512 + 32 * s + 8 * q); ckk = MFMA16(ak[s], bk, ckk); cqk = MFMA16(aq[s], bk, cqk); }
;                 const int j = 16 * tj + r; const float Gj = sG[j]; const int jpos = (j & 32) + perm32s(j & 31);
;                 f32x4 lv;
; #pragma unroll
;                 for (int e = 0; e < 4; ++e) { const int i = 16 * lw + 4 * q + e; const float Gi = sG[i], bi = sB[i];
;                     const float dec = (i >= j) ? __expf(Gi - Gj) : 0.f;
;                     lv[e] = (i > j) ? ckk[e] * bi * dec : 0.f;
;                     aqkp[i * 64 + jpos] = f2bf((i >= j) ? cqk[e] * dec : 0.f); }
;                 *(PG8_LAS f32x4*)(sL + j * 64 + 16 * lw + 4 * q) = lv;
;     ...
;             for (int k = 0; k < 16; ++k) { const int pidx = lane + 64 * k, i = pidx >> 4, pc = pidx & 15, aa = pc & 3, c32 = (pc >> 2) * 32;
;                 float f[8]; unpack8(*(const u32x4*)(qbase + (size_t)i * 512 + pc * 8), f); const float e = sE[i];
;                 u32x2 lo, hi; lo.x = pk2(f[0] * e, f[1] * e); lo.y = pk2(f[2] * e, f[3] * e); hi.x = pk2(f[4] * e, f[5] * e); hi.y = pk2(f[6] * e, f[7] * e);
;                 *(u32x2*)(qgp + i * 128 + c32 + 8 * ((2 * aa) & 3) + 4 * (aa >> 1)) = lo;
;                 *(u32x2*)(qgp + i * 128 + c32 + 8 * ((2 * aa + 1) & 3) + 4 * (aa >> 1)) = hi; }
;         } else {
;             const int d = (role - 2) * 64 + lane; float x[64];
; #pragma unroll
;             for (int c8 = 0; c8 < 8; ++c8) { float f[8]; unpack8(*(const u32x4*)(kTb + (size_t)d * 64 + 8 * c8), f);
; #pragma unroll
;                 for (int e = 0; e < 8; ++e) x[8 * c8 + e] = f[e] * sK[8 * c8 + e]; }
; #pragma unroll
;             for (int c8 = 0; c8 < 8; ++c8) { u32x4 o;
;                 o.x = pk2(x[tokofpos(8 * c8 + 0)], x[tokofpos(8 * c8 + 1)]); o.y = pk2(x[tokofpos(8 * c8 + 2)], x[tokofpos(8 * c8 + 3)]);
;                 o.z = pk2(x[tokofpos(8 * c8 + 4)], x[tokofpos(8 * c8 + 5)]); o.w = pk2(x[tokofpos(8 * c8 + 6)], x[tokofpos(8 * c8 + 7)]);
;                 *(u32x4*)(kdTp + d * 64 + 8 * c8) = o; }
	v_lshlrev_b32_e32 v19, 6, v37
	v_cndmask_b32_e64 v182, 0, 1.0, vcc
	v_cmp_eq_u32_e32 vcc, 42, v1
	v_writelane_b32 v252, s1, 10
	v_cmp_ge_u32_e64 s[0:1], v35, v3
	v_cndmask_b32_e64 v183, 0, 1.0, vcc
	v_cmp_eq_u32_e32 vcc, 43, v1
	v_writelane_b32 v252, s0, 11
	s_waitcnt vmcnt(2)
	v_lshlrev_b32_e32 v21, 6, v39
	v_cndmask_b32_e64 v184, 0, 1.0, vcc
	v_cmp_eq_u32_e32 vcc, 44, v1
	v_writelane_b32 v252, s1, 12
	v_cmp_lt_u32_e64 s[0:1], v37, v3
	v_cndmask_b32_e64 v185, 0, 1.0, vcc
	v_cmp_eq_u32_e32 vcc, 45, v1
	v_writelane_b32 v252, s0, 13
	v_or_b32_e32 v27, 4, v13
	v_cndmask_b32_e64 v186, 0, 1.0, vcc
	v_cmp_eq_u32_e32 vcc, 46, v1
	v_writelane_b32 v252, s1, 14
	v_cmp_ge_u32_e64 s[0:1], v37, v3
	v_cndmask_b32_e64 v187, 0, 1.0, vcc
	v_cmp_eq_u32_e32 vcc, 47, v1
	v_writelane_b32 v252, s0, 15
	v_or_b32_e32 v16, v7, v13
	v_cndmask_b32_e64 v188, 0, 1.0, vcc
	v_cmp_eq_u32_e32 vcc, 48, v1
	v_writelane_b32 v252, s1, 16
	v_cmp_gt_u32_e64 s[0:1], v37, v3
	v_cndmask_b32_e64 v189, 0, 1.0, vcc
	v_cmp_eq_u32_e32 vcc, 49, v1
	v_writelane_b32 v252, s0, 17
	v_or_b32_e32 v18, v9, v13
	v_cndmask_b32_e64 v190, 0, 1.0, vcc
	v_cmp_eq_u32_e32 vcc, 50, v1
	v_writelane_b32 v252, s1, 18
	v_cmp_lt_u32_e64 s[0:1], v39, v3
	v_cndmask_b32_e64 v191, 0, 1.0, vcc
	v_cmp_eq_u32_e32 vcc, 51, v1
	v_writelane_b32 v252, s0, 19
	v_or_b32_e32 v20, v19, v13
	v_cndmask_b32_e64 v192, 0, 1.0, vcc
	v_cmp_eq_u32_e32 vcc, 52, v1
	v_writelane_b32 v252, s1, 20
	v_cmp_ge_u32_e64 s[0:1], v39, v3
	v_cndmask_b32_e64 v193, 0, 1.0, vcc
	v_cmp_eq_u32_e32 vcc, 53, v1
	v_writelane_b32 v252, s0, 21
	v_or_b32_e32 v22, v21, v13
	v_cndmask_b32_e64 v194, 0, 1.0, vcc
	v_cmp_eq_u32_e32 vcc, 54, v1
	v_writelane_b32 v252, s1, 22
	v_cmp_gt_u32_e64 s[0:1], v39, v3
	v_cndmask_b32_e64 v195, 0, 1.0, vcc
	v_cmp_eq_u32_e32 vcc, 55, v1
	v_writelane_b32 v252, s0, 23
	v_or_b32_e32 v24, v7, v27
	v_cndmask_b32_e64 v196, 0, 1.0, vcc
	v_cmp_eq_u32_e32 vcc, 56, v1
	v_writelane_b32 v252, s1, 24
	v_cmp_ge_u32_e64 s[0:1], v33, v25
	v_cndmask_b32_e64 v197, 0, 1.0, vcc
	v_cmp_eq_u32_e32 vcc, 57, v1
	v_writelane_b32 v252, s0, 25
	v_or_b32_e32 v26, v9, v27
	v_or_b32_e32 v28, v19, v27
	v_or_b32_e32 v30, v21, v27
	v_or_b32_e32 v27, 32, v13
	v_or_b32_e32 v13, 36, v13
	v_cndmask_b32_e64 v198, 0, 1.0, vcc
	v_cmp_eq_u32_e32 vcc, 58, v1
	v_add_u32_e32 v17, s4, v2
	v_lshlrev_b32_e32 v2, 7, v3
	v_lshl_add_u32 v137, v3, 2, s4
	v_cmp_lt_u32_e64 s[12:13], v33, v3
	v_lshlrev_b32_e32 v23, 8, v3
	v_writelane_b32 v252, s1, 26
	v_cmp_gt_u32_e64 s[0:1], v33, v25
	v_or_b32_e32 v41, 32, v3
	v_or_b32_e32 v34, v9, v27
	v_or_b32_e32 v43, 48, v3
	v_or_b32_e32 v42, v9, v13
	v_cndmask_b32_e64 v199, 0, 1.0, vcc
	v_cmp_eq_u32_e32 vcc, 59, v1
	v_mul_u32_u24_e32 v9, 0x90, v3
	v_lshlrev_b32_e32 v3, 4, v3
	v_writelane_b32 v252, s0, 27
	v_cndmask_b32_e64 v200, 0, 1.0, vcc
	v_cmp_eq_u32_e32 vcc, 60, v1
	v_lshl_or_b32 v102, v5, 10, v3
	v_add_u32_e32 v3, s4, v0
	v_writelane_b32 v252, s1, 28
	v_cmp_lt_u32_e64 s[0:1], v35, v25
	v_cndmask_b32_e64 v201, 0, 1.0, vcc
	v_cmp_eq_u32_e32 vcc, 61, v1
	v_add_u32_e32 v206, 0x200, v3
	v_lshlrev_b32_e32 v3, 4, v152
	v_writelane_b32 v252, s0, 29
	v_cndmask_b32_e64 v202, 0, 1.0, vcc
	v_cmp_eq_u32_e32 vcc, 62, v1
	s_add_u32 s29, s16, 0x16000000
	v_and_b32_e32 v3, 0xc0, v3
	v_lshlrev_b32_e32 v98, 2, v1
	v_writelane_b32 v252, s1, 30
	v_cmp_eq_u32_e64 s[62:63], 0, v1
	v_cndmask_b32_e64 v203, 0, 1.0, vcc
	v_cmp_eq_u32_e32 vcc, 63, v1
	v_lshl_add_u32 v205, v1, 1, s4
	v_or_b32_e32 v1, 0x1f80, v11
	s_addc_u32 s30, s17, 0
	s_lshl_b32 s0, s33, 7
	v_lshl_or_b32 v3, v5, 8, v3
	v_and_b32_e32 v5, 1, v152
	v_lshlrev_b32_e32 v11, 2, v152
	v_writelane_b32 v252, s0, 31
	v_lshlrev_b32_e32 v5, 5, v5
	v_and_b32_e32 v11, 8, v11
	v_lshlrev_b64 v[100:101], 7, v[96:97]
	v_lshlrev_b32_e32 v14, 6, v96
	v_cmp_lt_u32_e64 s[36:37], v33, v25
	v_cmp_ge_u32_e64 s[44:45], v35, v25
	v_cmp_lt_u32_e64 s[46:47], v37, v25
	v_cmp_ge_u32_e64 s[48:49], v37, v25
	v_cmp_gt_u32_e64 s[50:51], v37, v25
	v_cmp_lt_u32_e64 s[52:53], v39, v25
	v_cmp_ge_u32_e64 s[54:55], v39, v25
	v_cmp_gt_u32_e64 s[56:57], v39, v25
	v_lshlrev_b32_e32 v25, 8, v25
	v_or_b32_e32 v32, v7, v27
	v_or_b32_e32 v36, v19, v27
	v_or_b32_e32 v38, v21, v27
	v_lshlrev_b32_e32 v27, 8, v41
	v_or_b32_e32 v40, v7, v13
	v_or_b32_e32 v44, v19, v13
	v_or_b32_e32 v46, v21, v13
	v_lshlrev_b32_e32 v7, 8, v43
	v_or_b32_e32 v48, 0x800, v2
	v_or_b32_e32 v50, 0x1000, v2
	v_or_b32_e32 v52, 0x1800, v2
	v_or3_b32 v96, v3, v5, v11
	s_mov_b64 s[0:1], 0x16004800
	v_writelane_b32 v252, s4, 32
	s_mov_b32 s15, 0
	v_add_u32_e32 v130, s4, v98
	v_lshl_add_u32 v138, v33, 2, s4
	v_cmp_lt_u32_e64 s[58:59], v33, v41
	v_cmp_ge_u32_e64 s[60:61], v33, v41
	v_cndmask_b32_e64 v139, 0, 1.0, s[62:63]
	v_cndmask_b32_e64 v204, 0, 1.0, vcc
	v_mov_b32_e32 v103, v97
	s_lshl_b32 s31, s82, 3
	s_mov_b64 s[74:75], s[80:81]
	s_mov_b32 s34, 2
	v_lshl_add_u64 v[104:105], v[96:97], 0, s[0:1]
	v_lshlrev_b32_e32 v106, 1, v8
	v_lshlrev_b32_e32 v96, 1, v12
	v_lshlrev_b32_e32 v108, 1, v6
	v_lshlrev_b32_e32 v207, 1, v16
	v_lshlrev_b32_e32 v208, 1, v18
	v_lshlrev_b32_e32 v209, 1, v20
	v_lshlrev_b32_e32 v210, 1, v22
	v_add_u32_e32 v211, v15, v23
	v_lshlrev_b32_e32 v212, 1, v24
	v_lshlrev_b32_e32 v213, 1, v26
	v_lshlrev_b32_e32 v214, 1, v28
	v_lshlrev_b32_e32 v215, 1, v30
	v_add_u32_e32 v216, v15, v25
	v_lshlrev_b32_e32 v217, 1, v32
	v_lshlrev_b32_e32 v218, 1, v34
	v_lshlrev_b32_e32 v219, 1, v36
	v_lshlrev_b32_e32 v220, 1, v38
	v_add_u32_e32 v221, v15, v27
	s_mov_b32 s35, 0xc000
	v_lshlrev_b32_e32 v222, 1, v40
	v_lshlrev_b32_e32 v223, 1, v42
	v_lshlrev_b32_e32 v224, 1, v44
	v_lshlrev_b32_e32 v225, 1, v46
	v_add_u32_e32 v226, v15, v7
	v_lshlrev_b32_e32 v110, 1, v14
	v_add_u32_e32 v227, s4, v1
	v_add_u32_e32 v228, v17, v9
	v_lshlrev_b32_e32 v112, 1, v0
	v_lshlrev_b32_e32 v114, 1, v10
	v_lshlrev_b32_e32 v116, 1, v4
	v_lshlrev_b32_e32 v118, 1, v2
	v_lshlrev_b32_e32 v120, 1, v48
	v_lshlrev_b32_e32 v122, 1, v50
	v_lshlrev_b32_e32 v124, 1, v52
	v_mov_b32_e32 v229, 0x12000
	v_writelane_b32 v252, s82, 33
	s_lshl_b32 s38, s82, 2
	s_add_i32 s98, s38, 4
	v_cmp_gt_u32_e64 s[64:65], v33, v41
	v_cmp_lt_u32_e64 s[66:67], v35, v41
	v_cmp_ge_u32_e64 s[68:69], v35, v41
	v_cmp_lt_u32_e64 s[70:71], v37, v41
	v_cmp_ge_u32_e64 s[72:73], v37, v41
	v_cmp_gt_u32_e64 s[42:43], v37, v41
	v_cmp_lt_u32_e64 s[76:77], v39, v41
	v_cmp_ge_u32_e64 s[78:79], v39, v41
	v_cmp_gt_u32_e64 s[80:81], v39, v41
	v_cmp_lt_u32_e64 s[82:83], v33, v43
	v_cmp_ge_u32_e64 s[84:85], v33, v43
	v_cmp_gt_u32_e64 s[86:87], v33, v43
	v_cmp_lt_u32_e64 s[88:89], v35, v43
	v_cmp_ge_u32_e64 s[90:91], v35, v43
	v_cmp_lt_u32_e64 s[92:93], v37, v43
	v_cmp_ge_u32_e64 s[94:95], v37, v43
	v_cmp_gt_u32_e64 s[96:97], v37, v43
	v_cmp_lt_u32_e64 s[0:1], v39, v43
	v_cmp_ge_u32_e64 s[6:7], v39, v43
	v_cmp_gt_u32_e64 s[4:5], v39, v43
	s_branch .LBB0_253
; __device__ __forceinline__ void phase_prep(const Args& a, PG8_LAS unsigned char* lds) {
;     ...
;         for (int s = 0; s < 4; ++s) { ak[s] = *(const bf16x8*)(kbase + (size_t)(16 * lw + r) * 512 + 32 * s + 8 * q); aq[s] = *(const bf16x8*)(qbase + (size_t)(16 * lw + r) * 512 + 32 * s + 8 * q); }
; #pragma unroll
;         for (int tj = 0; tj < 2; ++tj)
; #pragma unroll
;             for (int s = 0; s < 4; ++s) bkf[tj][s] = *(const bf16x8*)(kbase + (size_t)(16 * tj + r) * 512 + 32 * s + 8 * q);
;         bf16x8 pv[2][2], pk[2][2];
;         if (role != 0) {
; #pragma unroll
;         for (int cc = 0; cc < 2; ++cc) { const int ct = 2 * lw + cc;
;             pv[cc][0] = *(const bf16x8*)(vTb + (size_t)(16 * ct + r) * 64 + 8 * q); pv[cc][1] = *(const bf16x8*)(vTb + (size_t)(16 * ct + r) * 64 + 32 + 8 * q);
;     ...
;         {
;             bf16x8 tf[4][2];
; #pragma unroll
;             for (int it = 0; it < 4; ++it)
; #pragma unroll
;                 for (int s = 0; s < 2; ++s) tf[it][s] = *(const PG8_LAS bf16x8*)(Tu + ((16 * it + r) * 72 + 32 * s + 8 * q) * 2);
; #pragma unroll
;             for (int cc = 0; cc < 2; ++cc) { const int ct = 2 * lw + cc;
;                 const bf16x8 v0 = pv[cc][0], v1 = pv[cc][1];
; #pragma unroll
;                 for (int it = 0; it < 4; ++it) { f32x4 acc = {0.f, 0.f, 0.f, 0.f}; acc = MFMA16(tf[it][0], v0, acc); acc = MFMA16(tf[it][1], v1, acc);
;                     u32x2 w; w.x = pk2c(acc[0], acc[1]); w.y = pk2c(acc[2], acc[3]);
;                     *(u32x2*)(uT + (16 * ct + r) * 64 + 16 * it + 4 * q) = w; } }
; #pragma unroll
;             for (int it = 0; it < 4; ++it)
; #pragma unroll
;                 for (int s = 0; s < 2; ++s) tf[it][s] = *(const PG8_LAS bf16x8*)(Tw + ((16 * it + r) * 72 + 32 * s + 8 * q) * 2);
; #pragma unroll
;             for (int cc = 0; cc < 2; ++cc) { const int dt = 2 * lw + cc;
;                 const bf16x8 k0 = pk[cc][0], k1 = pk[cc][1];
;                 const int o4 = 16 * dt + 4 * q, dpos = (o4 & ~31) + perm32s(o4 & 31);
; #pragma unroll
;                 for (int it = 0; it < 4; ++it) { f32x4 acc = {0.f, 0.f, 0.f, 0.f}; acc = MFMA16(k0, tf[it][0], acc); acc = MFMA16(k1, tf[it][1], acc);
;                     u32x2 w; w.x = pk2c(acc[0], acc[1]); w.y = pk2c(acc[2], acc[3]);
;                     *(u32x2*)(wp + (16 * it + r) * 128 + dpos) = w; } }
;         }
.LBB0_252:
	s_waitcnt lgkmcnt(0)
	s_barrier
	v_readlane_b32 s40, v253, 53
	v_readlane_b32 s41, v253, 54
	s_andn2_b64 vcc, exec, s[40:41]
	s_cbranch_vccnz .Lst4_r0
	ds_read_b128 v[32:35], v228 offset:17408
	ds_read_b128 v[36:39], v228 offset:17472
	ds_read_b128 v[44:47], v228 offset:19712
	ds_read_b128 v[48:51], v228 offset:19776
	ds_read_b128 v[56:59], v228 offset:22016
	ds_read_b128 v[60:63], v228 offset:22080
	s_waitcnt lgkmcnt(5)
	v_mfma_f32_16x16x32_bf16 v[40:43], v[32:35], v[0:3], 0
	ds_read_b128 v[68:71], v228 offset:24320
	ds_read_b128 v[72:75], v228 offset:24384
	v_mov_b32_e32 v113, v97
	v_mfma_f32_16x16x32_bf16 v[32:35], v[32:35], v[20:23], 0
	v_mov_b32_e32 v115, v97
	s_mov_b64 s[20:21], 0xc000
	v_mov_b32_e32 v117, v97
	s_waitcnt lgkmcnt(6)
	v_mfma_f32_16x16x32_bf16 v[40:43], v[36:39], v[4:7], v[40:43]
	v_mov_b32_e32 v121, v97
	v_mov_b32_e32 v123, v97
	v_mov_b32_e32 v119, v97
	s_waitcnt lgkmcnt(5)
	v_mfma_f32_16x16x32_bf16 v[52:55], v[44:47], v[0:3], 0
	v_mov_b32_e32 v125, v97
	s_add_i32 s38, s38, 1
	s_add_i32 s31, s31, s34
	v_mfma_f32_16x16x32_bf16 v[32:35], v[36:39], v[28:31], v[32:35]
	v_lshl_add_u64 v[36:37], s[18:19], 0, v[112:113]
	v_lshl_add_u64 v[80:81], v[36:37], 0, v[114:115]
	v_lshl_add_u64 v[82:83], v[80:81], 0, s[20:21]
	s_waitcnt lgkmcnt(3)
	v_mfma_f32_16x16x32_bf16 v[64:67], v[56:59], v[0:3], 0
	s_cmp_lt_i32 s38, s98
	v_mfma_f32_16x16x32_bf16 v[36:39], v[44:47], v[20:23], 0
	v_cvt_pk_bf16_f32 v44, v40, v41
	v_cvt_pk_bf16_f32 v45, v42, v43
	v_add_co_u32_e32 v46, vcc, s35, v80
	v_mfma_f32_16x16x32_bf16 v[40:43], v[56:59], v[20:23], 0
	s_nop 0
	v_addc_co_u32_e32 v47, vcc, 0, v81, vcc
	s_mov_b32 s99, 0
	s_cmp_lt_i32 s38, s98
	s_cbranch_scc0 .Lpf_none_a
	s_ashr_i32 vcc_lo, s38, 1
	s_ashr_i32 vcc_hi, vcc_lo, 31
	s_lshl_b32 s14, s38, 1
	s_and_b32 s14, s14, 2
	s_add_i32 s26, s14, s33
	s_lshl_b64 s[24:25], vcc, 16
	s_lshl_b64 s[100:101], vcc, 8
	v_mov_b32_e32 v129, s101
	v_or_b32_e32 v128, s100, v98
	s_mov_b32 s100, s26
	s_mov_b32 s101, s15
	v_lshl_add_u64 v[128:129], v[128:129], 0, s[100:101]
	v_readlane_b32 s14, v253, 43
	s_add_u32 s22, s14, s24
	v_readlane_b32 s14, v253, 44
	s_addc_u32 s23, s14, s25
	s_lshl_b32 s27, s26, 8
	s_add_u32 s22, s22, s27
	s_addc_u32 s23, s23, 0
	v_readlane_b32 s39, v253, 45
	s_add_u32 s39, s39, s24
	v_readlane_b32 s40, v253, 46
	s_addc_u32 s40, s40, s25
	s_add_u32 vcc_lo, s39, s27
	s_addc_u32 vcc_hi, s40, 0
	v_mov_b32_e32 v107, v97
	v_lshl_add_u64 v[230:231], vcc, 0, v[106:107]
	v_lshl_add_u64 v[232:233], s[22:23], 0, v[106:107]
	v_lshl_add_u64 v[230:231], v[230:231], 0, v[96:97]
	v_lshl_add_u64 v[232:233], v[232:233], 0, v[96:97]
	v_lshl_add_u64 v[126:127], v[128:129], 2, s[8:9]
	global_load_dword v234, v[126:127], off
	v_readlane_b32 s100, v253, 49
	v_readlane_b32 s101, v253, 50
	s_nop 1
	v_lshl_add_u64 v[126:127], v[128:129], 2, s[100:101]
	global_load_dword v111, v[126:127], off
	global_load_dwordx4 v[84:87], v[230:231], off
	global_load_dwordx4 v[88:91], v[230:231], off offset:64
	global_load_dwordx4 v[240:243], v[232:233], off
	global_load_dwordx4 v[244:247], v[232:233], off offset:64
	global_load_dwordx4 v[92:95], v[230:231], off offset:128
	global_load_dwordx4 v[236:239], v[230:231], off offset:192
	global_load_dwordx4 v[248:251], v[232:233], off offset:128
	global_load_dwordx4 v[126:129], v[232:233], off offset:192
	s_mov_b32 s99, 1
.Lpf_none_a:
	s_cmp_lt_i32 s38, s98
	global_store_dwordx2 v[46:47], v[44:45], off
	v_mfma_f32_16x16x32_bf16 v[52:55], v[48:51], v[4:7], v[52:55]
	v_lshl_add_u64 v[80:81], s[18:19], 0, v[116:117]
	s_waitcnt lgkmcnt(2)
	v_mfma_f32_16x16x32_bf16 v[64:67], v[60:63], v[4:7], v[64:67]
	v_mfma_f32_16x16x32_bf16 v[40:43], v[60:63], v[28:31], v[40:43]
	v_cvt_pk_bf16_f32 v60, v32, v33
	v_cvt_pk_bf16_f32 v61, v34, v35
	ds_read_b128 v[32:35], v228 offset:28928
	v_mfma_f32_16x16x32_bf16 v[36:39], v[48:51], v[28:31], v[36:39]
	v_cvt_pk_bf16_f32 v44, v52, v53
	v_cvt_pk_bf16_f32 v45, v54, v55
	global_store_dwordx2 v[82:83], v[44:45], off offset:32
	s_waitcnt lgkmcnt(2)
	v_mfma_f32_16x16x32_bf16 v[76:79], v[68:71], v[0:3], 0
	global_store_dwordx2 v[82:83], v[60:61], off offset:2048
	ds_read_b128 v[60:63], v228 offset:28992
	v_cvt_pk_bf16_f32 v48, v64, v65
	v_mfma_f32_16x16x32_bf16 v[44:47], v[68:71], v[20:23], 0
	v_cvt_pk_bf16_f32 v49, v66, v67
	v_cvt_pk_bf16_f32 v36, v36, v37
	v_cvt_pk_bf16_f32 v37, v38, v39
	s_waitcnt lgkmcnt(1)
	v_mfma_f32_16x16x32_bf16 v[64:67], v[8:11], v[32:35], 0
	global_store_dwordx2 v[82:83], v[36:37], off offset:2080
	ds_read_b128 v[36:39], v228 offset:31232
	global_store_dwordx2 v[82:83], v[48:49], off offset:64
	v_mfma_f32_16x16x32_bf16 v[32:35], v[16:19], v[32:35], 0
	ds_read_b128 v[48:51], v228 offset:26624
	v_mfma_f32_16x16x32_bf16 v[76:79], v[72:75], v[4:7], v[76:79]
	v_mfma_f32_16x16x32_bf16 v[44:47], v[72:75], v[28:31], v[44:47]
	v_cvt_pk_bf16_f32 v72, v40, v41
	v_cvt_pk_bf16_f32 v73, v42, v43
	global_store_dwordx2 v[82:83], v[72:73], off offset:2112
	ds_read_b128 v[72:75], v228 offset:33536
	s_waitcnt lgkmcnt(3)
	v_mfma_f32_16x16x32_bf16 v[64:67], v[12:15], v[60:63], v[64:67]
	s_nop 0
	v_cvt_pk_bf16_f32 v52, v76, v77
	v_cvt_pk_bf16_f32 v53, v78, v79
	ds_read_b128 v[40:43], v228 offset:31296
	v_mfma_f32_16x16x32_bf16 v[32:35], v[24:27], v[60:63], v[32:35]
	v_cvt_pk_bf16_f32 v44, v44, v45
	v_cvt_pk_bf16_f32 v45, v46, v47
	global_store_dwordx2 v[82:83], v[52:53], off offset:96
	ds_read_b128 v[52:55], v228 offset:26688
	s_waitcnt lgkmcnt(4)
	v_mfma_f32_16x16x32_bf16 v[68:71], v[8:11], v[36:39], 0
	global_store_dwordx2 v[82:83], v[44:45], off offset:2144
	ds_read_b128 v[44:47], v228 offset:33600
	v_cvt_pk_bf16_f32 v64, v64, v65
	v_mfma_f32_16x16x32_bf16 v[36:39], v[16:19], v[36:39], 0
	v_cvt_pk_bf16_f32 v65, v66, v67
	v_cvt_pk_bf16_f32 v66, v32, v33
	v_cvt_pk_bf16_f32 v67, v34, v35
	s_waitcnt lgkmcnt(4)
; __device__ __forceinline__ void phase_prep(const Args& a, PG8_LAS unsigned char* lds) {
;     ...
;         for (int s = 0; s < 4; ++s) { ak[s] = *(const bf16x8*)(kbase + (size_t)(16 * lw + r) * 512 + 32 * s + 8 * q); aq[s] = *(const bf16x8*)(qbase + (size_t)(16 * lw + r) * 512 + 32 * s + 8 * q); }
; #pragma unroll
;         for (int tj = 0; tj < 2; ++tj)
; #pragma unroll
;             for (int s = 0; s < 4; ++s) bkf[tj][s] = *(const bf16x8*)(kbase + (size_t)(16 * tj + r) * 512 + 32 * s + 8 * q);
;         bf16x8 pv[2][2], pk[2][2];
;         if (role != 0) {
; #pragma unroll
;         for (int cc = 0; cc < 2; ++cc) { const int ct = 2 * lw + cc;
;             pv[cc][0] = *(const bf16x8*)(vTb + (size_t)(16 * ct + r) * 64 + 8 * q); pv[cc][1] = *(const bf16x8*)(vTb + (size_t)(16 * ct + r) * 64 + 32 + 8 * q);
;     ...
;         {
;             bf16x8 tf[4][2];
; #pragma unroll
;             for (int it = 0; it < 4; ++it)
; #pragma unroll
;                 for (int s = 0; s < 2; ++s) tf[it][s] = *(const PG8_LAS bf16x8*)(Tu + ((16 * it + r) * 72 + 32 * s + 8 * q) * 2);
; #pragma unroll
;             for (int cc = 0; cc < 2; ++cc) { const int ct = 2 * lw + cc;
;                 const bf16x8 v0 = pv[cc][0], v1 = pv[cc][1];
; #pragma unroll
;                 for (int it = 0; it < 4; ++it) { f32x4 acc = {0.f, 0.f, 0.f, 0.f}; acc = MFMA16(tf[it][0], v0, acc); acc = MFMA16(tf[it][1], v1, acc);
;                     u32x2 w; w.x = pk2c(acc[0], acc[1]); w.y = pk2c(acc[2], acc[3]);
;                     *(u32x2*)(uT + (16 * ct + r) * 64 + 16 * it + 4 * q) = w; } }
; #pragma unroll
;             for (int it = 0; it < 4; ++it)
; #pragma unroll
;                 for (int s = 0; s < 2; ++s) tf[it][s] = *(const PG8_LAS bf16x8*)(Tw + ((16 * it + r) * 72 + 32 * s + 8 * q) * 2);
; #pragma unroll
;             for (int cc = 0; cc < 2; ++cc) { const int dt = 2 * lw + cc;
;                 const bf16x8 k0 = pk[cc][0], k1 = pk[cc][1];
;                 const int o4 = 16 * dt + 4 * q, dpos = (o4 & ~31) + perm32s(o4 & 31);
; #pragma unroll
;                 for (int it = 0; it < 4; ++it) { f32x4 acc = {0.f, 0.f, 0.f, 0.f}; acc = MFMA16(k0, tf[it][0], acc); acc = MFMA16(k1, tf[it][1], acc);
;                     u32x2 w; w.x = pk2c(acc[0], acc[1]); w.y = pk2c(acc[2], acc[3]);
;                     *(u32x2*)(wp + (16 * it + r) * 128 + dpos) = w; } }
;         }
	v_mfma_f32_16x16x32_bf16 v[56:59], v[8:11], v[48:51], 0
	v_lshl_add_u64 v[82:83], v[80:81], 0, v[118:119]
	v_lshl_add_u64 v[60:61], v[80:81], 0, v[124:125]
	s_waitcnt lgkmcnt(3)
	v_mfma_f32_16x16x32_bf16 v[76:79], v[8:11], v[72:75], 0
	v_mfma_f32_16x16x32_bf16 v[48:51], v[16:19], v[48:51], 0
	v_mfma_f32_16x16x32_bf16 v[32:35], v[16:19], v[72:75], 0
	s_waitcnt lgkmcnt(2)
	v_mfma_f32_16x16x32_bf16 v[68:71], v[12:15], v[40:43], v[68:71]
	v_mfma_f32_16x16x32_bf16 v[36:39], v[24:27], v[40:43], v[36:39]
	s_waitcnt lgkmcnt(1)
	v_mfma_f32_16x16x32_bf16 v[56:59], v[12:15], v[52:55], v[56:59]
	s_waitcnt lgkmcnt(0)
	v_mfma_f32_16x16x32_bf16 v[76:79], v[12:15], v[44:47], v[76:79]
	v_mfma_f32_16x16x32_bf16 v[48:51], v[24:27], v[52:55], v[48:51]
	v_lshl_add_u64 v[54:55], v[80:81], 0, v[120:121]
	s_nop 0
	v_cvt_pk_bf16_f32 v52, v68, v69
	v_cvt_pk_bf16_f32 v53, v70, v71
	v_mfma_f32_16x16x32_bf16 v[32:35], v[24:27], v[44:47], v[32:35]
	v_lshl_add_u64 v[70:71], v[80:81], 0, v[122:123]
	global_store_dwordx4 v[54:55], v[64:67], off
	v_cvt_pk_bf16_f32 v54, v36, v37
	v_cvt_pk_bf16_f32 v55, v38, v39
	v_cvt_pk_bf16_f32 v56, v56, v57
	v_cvt_pk_bf16_f32 v57, v58, v59
	v_cvt_pk_bf16_f32 v68, v76, v77
	v_cvt_pk_bf16_f32 v69, v78, v79
	v_cvt_pk_bf16_f32 v58, v48, v49
	v_cvt_pk_bf16_f32 v59, v50, v51
	global_store_dwordx4 v[70:71], v[52:55], off
	v_cvt_pk_bf16_f32 v70, v32, v33
	v_cvt_pk_bf16_f32 v71, v34, v35
	global_store_dwordx4 v[82:83], v[56:59], off
	global_store_dwordx4 v[60:61], v[68:71], off
	s_branch .Lst4_end
.Lst4_r0:
	ds_read_b128 v[32:35], v228 offset:17408
	ds_read_b128 v[36:39], v228 offset:17472
	ds_read_b128 v[44:47], v228 offset:19712
	ds_read_b128 v[48:51], v228 offset:19776
	ds_read_b128 v[56:59], v228 offset:22016
	ds_read_b128 v[60:63], v228 offset:22080
	s_waitcnt vmcnt(7) lgkmcnt(5)
	v_mfma_f32_16x16x32_bf16 v[40:43], v[32:35], v[0:3], 0
	ds_read_b128 v[68:71], v228 offset:24320
	ds_read_b128 v[72:75], v228 offset:24384
	v_mov_b32_e32 v113, v97
	s_waitcnt vmcnt(3)
	v_mfma_f32_16x16x32_bf16 v[32:35], v[32:35], v[20:23], 0
	v_mov_b32_e32 v115, v97
	s_mov_b64 s[20:21], 0xc000
	v_mov_b32_e32 v117, v97
	s_waitcnt lgkmcnt(6)
	v_mfma_f32_16x16x32_bf16 v[40:43], v[36:39], v[4:7], v[40:43]
	v_mov_b32_e32 v121, v97
	v_mov_b32_e32 v123, v97
	v_mov_b32_e32 v119, v97
	s_waitcnt lgkmcnt(5)
	v_mfma_f32_16x16x32_bf16 v[52:55], v[44:47], v[0:3], 0
	v_mov_b32_e32 v125, v97
	s_add_i32 s38, s38, 1
	s_add_i32 s31, s31, s34
	s_waitcnt vmcnt(2)
	v_mfma_f32_16x16x32_bf16 v[32:35], v[36:39], v[28:31], v[32:35]
	v_lshl_add_u64 v[36:37], s[18:19], 0, v[112:113]
	v_lshl_add_u64 v[80:81], v[36:37], 0, v[114:115]
	v_lshl_add_u64 v[82:83], v[80:81], 0, s[20:21]
	s_waitcnt lgkmcnt(3)
	v_mfma_f32_16x16x32_bf16 v[64:67], v[56:59], v[0:3], 0
	s_cmp_lt_i32 s38, s98
	v_mfma_f32_16x16x32_bf16 v[36:39], v[44:47], v[20:23], 0
	v_cvt_pk_bf16_f32 v44, v40, v41
	v_cvt_pk_bf16_f32 v45, v42, v43
	v_add_co_u32_e32 v46, vcc, s35, v80
	v_mfma_f32_16x16x32_bf16 v[40:43], v[56:59], v[20:23], 0
	s_nop 0
	v_addc_co_u32_e32 v47, vcc, 0, v81, vcc
	global_store_dwordx2 v[46:47], v[44:45], off
	v_mfma_f32_16x16x32_bf16 v[52:55], v[48:51], v[4:7], v[52:55]
	v_lshl_add_u64 v[80:81], s[18:19], 0, v[116:117]
	s_waitcnt lgkmcnt(2)
	v_mfma_f32_16x16x32_bf16 v[64:67], v[60:63], v[4:7], v[64:67]
	v_mfma_f32_16x16x32_bf16 v[40:43], v[60:63], v[28:31], v[40:43]
	v_cvt_pk_bf16_f32 v60, v32, v33
	v_cvt_pk_bf16_f32 v61, v34, v35
	ds_read_b128 v[32:35], v228 offset:28928
	v_mfma_f32_16x16x32_bf16 v[36:39], v[48:51], v[28:31], v[36:39]
	v_cvt_pk_bf16_f32 v44, v52, v53
	v_cvt_pk_bf16_f32 v45, v54, v55
	global_store_dwordx2 v[82:83], v[44:45], off offset:32
	s_waitcnt lgkmcnt(2)
	v_mfma_f32_16x16x32_bf16 v[76:79], v[68:71], v[0:3], 0
	global_store_dwordx2 v[82:83], v[60:61], off offset:2048
	ds_read_b128 v[60:63], v228 offset:28992
	v_cvt_pk_bf16_f32 v48, v64, v65
	v_mfma_f32_16x16x32_bf16 v[44:47], v[68:71], v[20:23], 0
	v_cvt_pk_bf16_f32 v49, v66, v67
	v_cvt_pk_bf16_f32 v36, v36, v37
	v_cvt_pk_bf16_f32 v37, v38, v39
	s_waitcnt lgkmcnt(1)
	v_mfma_f32_16x16x32_bf16 v[64:67], v[8:11], v[32:35], 0
	global_store_dwordx2 v[82:83], v[36:37], off offset:2080
	ds_read_b128 v[36:39], v228 offset:31232
	global_store_dwordx2 v[82:83], v[48:49], off offset:64
	s_waitcnt vmcnt(6)
	v_mfma_f32_16x16x32_bf16 v[32:35], v[16:19], v[32:35], 0
	ds_read_b128 v[48:51], v228 offset:26624
	v_mfma_f32_16x16x32_bf16 v[76:79], v[72:75], v[4:7], v[76:79]
	v_mfma_f32_16x16x32_bf16 v[44:47], v[72:75], v[28:31], v[44:47]
	v_cvt_pk_bf16_f32 v72, v40, v41
	v_cvt_pk_bf16_f32 v73, v42, v43
	global_store_dwordx2 v[82:83], v[72:73], off offset:2112
	ds_read_b128 v[72:75], v228 offset:33536
	s_waitcnt lgkmcnt(3)
	v_mfma_f32_16x16x32_bf16 v[64:67], v[12:15], v[60:63], v[64:67]
	s_nop 0
	v_cvt_pk_bf16_f32 v52, v76, v77
	v_cvt_pk_bf16_f32 v53, v78, v79
	ds_read_b128 v[40:43], v228 offset:31296
	s_waitcnt vmcnt(6)
	s_mov_b32 s99, 0
	s_cmp_lt_i32 s38, s98
	s_cbranch_scc0 .Lpf_none_b
	s_ashr_i32 vcc_lo, s38, 1
	s_ashr_i32 vcc_hi, vcc_lo, 31
	s_lshl_b32 s14, s38, 1
	s_and_b32 s14, s14, 2
	s_add_i32 s26, s14, s33
	s_lshl_b64 s[24:25], vcc, 16
	s_lshl_b64 s[100:101], vcc, 8
	v_mov_b32_e32 v129, s101
	v_or_b32_e32 v128, s100, v98
	s_mov_b32 s100, s26
	s_mov_b32 s101, s15
	v_lshl_add_u64 v[128:129], v[128:129], 0, s[100:101]
	v_readlane_b32 s14, v253, 43
	s_add_u32 s22, s14, s24
	v_readlane_b32 s14, v253, 44
	s_addc_u32 s23, s14, s25
	s_lshl_b32 s27, s26, 8
	s_add_u32 s22, s22, s27
	s_addc_u32 s23, s23, 0
	v_readlane_b32 s39, v253, 45
	s_add_u32 s39, s39, s24
	v_readlane_b32 s40, v253, 46
	s_addc_u32 s40, s40, s25
	s_add_u32 vcc_lo, s39, s27
	s_addc_u32 vcc_hi, s40, 0
	v_mov_b32_e32 v107, v97
	v_lshl_add_u64 v[230:231], vcc, 0, v[106:107]
	v_lshl_add_u64 v[232:233], s[22:23], 0, v[106:107]
	v_lshl_add_u64 v[230:231], v[230:231], 0, v[96:97]
	v_lshl_add_u64 v[232:233], v[232:233], 0, v[96:97]
	v_lshl_add_u64 v[126:127], v[128:129], 2, s[8:9]
	global_load_dword v234, v[126:127], off
	v_readlane_b32 s100, v253, 49
	v_readlane_b32 s101, v253, 50
	s_nop 1
	v_lshl_add_u64 v[126:127], v[128:129], 2, s[100:101]
	global_load_dword v111, v[126:127], off
	global_load_dwordx4 v[84:87], v[230:231], off
	global_load_dwordx4 v[88:91], v[230:231], off offset:64
	global_load_dwordx4 v[240:243], v[232:233], off
	global_load_dwordx4 v[244:247], v[232:233], off offset:64
	global_load_dwordx4 v[92:95], v[230:231], off offset:128
	global_load_dwordx4 v[236:239], v[230:231], off offset:192
	global_load_dwordx4 v[248:251], v[232:233], off offset:128
	global_load_dwordx4 v[126:129], v[232:233], off offset:192
	s_mov_b32 s99, 1
; #define PG8_LAS __attribute__((address_space(3)))
; __device__ __forceinline__ unsigned pk2c(float a, float b) { const f32x2_ v = {a, b}; const bf16x2_ r = __builtin_convertvector(v, bf16x2_); return __builtin_bit_cast(unsigned, r); }
; #define MFMA16(a, b, c) __builtin_amdgcn_mfma_f32_16x16x32_bf16((a), (b), (c), 0, 0, 0)
; __device__ __forceinline__ void phase_prep(const Args& a, PG8_LAS unsigned char* lds) {
;     ...
;             for (int it = 0; it < 4; ++it)
; #pragma unroll
;                 for (int s = 0; s < 2; ++s) tf[it][s] = *(const PG8_LAS bf16x8*)(Tw + ((16 * it + r) * 72 + 32 * s + 8 * q) * 2);
; #pragma unroll
;             for (int cc = 0; cc < 2; ++cc) { const int dt = 2 * lw + cc;
;                 const bf16x8 k0 = pk[cc][0], k1 = pk[cc][1];
;                 const int o4 = 16 * dt + 4 * q, dpos = (o4 & ~31) + perm32s(o4 & 31);
; #pragma unroll
;                 for (int it = 0; it < 4; ++it) { f32x4 acc = {0.f, 0.f, 0.f, 0.f}; acc = MFMA16(k0, tf[it][0], acc); acc = MFMA16(k1, tf[it][1], acc);
;                     u32x2 w; w.x = pk2c(acc[0], acc[1]); w.y = pk2c(acc[2], acc[3]);
;                     *(u32x2*)(wp + (16 * it + r) * 128 + dpos) = w; } }
;         }
.Lpf_none_b:
	s_cmp_lt_i32 s38, s98
	v_mfma_f32_16x16x32_bf16 v[32:35], v[24:27], v[60:63], v[32:35]
	v_cvt_pk_bf16_f32 v44, v44, v45
	v_cvt_pk_bf16_f32 v45, v46, v47
	global_store_dwordx2 v[82:83], v[52:53], off offset:96
	ds_read_b128 v[52:55], v228 offset:26688
	s_waitcnt lgkmcnt(4)
	v_mfma_f32_16x16x32_bf16 v[68:71], v[8:11], v[36:39], 0
	global_store_dwordx2 v[82:83], v[44:45], off offset:2144
	ds_read_b128 v[44:47], v228 offset:33600
	v_cvt_pk_bf16_f32 v64, v64, v65
	v_mfma_f32_16x16x32_bf16 v[36:39], v[16:19], v[36:39], 0
	v_cvt_pk_bf16_f32 v65, v66, v67
	v_cvt_pk_bf16_f32 v66, v32, v33
	v_cvt_pk_bf16_f32 v67, v34, v35
	s_waitcnt lgkmcnt(4)
	v_mfma_f32_16x16x32_bf16 v[56:59], v[8:11], v[48:51], 0
	v_lshl_add_u64 v[82:83], v[80:81], 0, v[118:119]
	v_lshl_add_u64 v[60:61], v[80:81], 0, v[124:125]
	s_waitcnt lgkmcnt(3)
	v_mfma_f32_16x16x32_bf16 v[76:79], v[8:11], v[72:75], 0
	v_mfma_f32_16x16x32_bf16 v[48:51], v[16:19], v[48:51], 0
	v_mfma_f32_16x16x32_bf16 v[32:35], v[16:19], v[72:75], 0
	s_waitcnt lgkmcnt(2)
	v_mfma_f32_16x16x32_bf16 v[68:71], v[12:15], v[40:43], v[68:71]
	v_mfma_f32_16x16x32_bf16 v[36:39], v[24:27], v[40:43], v[36:39]
	s_waitcnt lgkmcnt(1)
	v_mfma_f32_16x16x32_bf16 v[56:59], v[12:15], v[52:55], v[56:59]
	s_waitcnt lgkmcnt(0)
	v_mfma_f32_16x16x32_bf16 v[76:79], v[12:15], v[44:47], v[76:79]
	v_mfma_f32_16x16x32_bf16 v[48:51], v[24:27], v[52:55], v[48:51]
	v_lshl_add_u64 v[54:55], v[80:81], 0, v[120:121]
	s_nop 0
	v_cvt_pk_bf16_f32 v52, v68, v69
	v_cvt_pk_bf16_f32 v53, v70, v71
	v_mfma_f32_16x16x32_bf16 v[32:35], v[24:27], v[44:47], v[32:35]
	v_lshl_add_u64 v[70:71], v[80:81], 0, v[122:123]
	global_store_dwordx4 v[54:55], v[64:67], off
	v_cvt_pk_bf16_f32 v54, v36, v37
	v_cvt_pk_bf16_f32 v55, v38, v39
	v_cvt_pk_bf16_f32 v56, v56, v57
	v_cvt_pk_bf16_f32 v57, v58, v59
	v_cvt_pk_bf16_f32 v68, v76, v77
	v_cvt_pk_bf16_f32 v69, v78, v79
	v_cvt_pk_bf16_f32 v58, v48, v49
	v_cvt_pk_bf16_f32 v59, v50, v51
	global_store_dwordx4 v[70:71], v[52:55], off
	v_cvt_pk_bf16_f32 v70, v32, v33
	v_cvt_pk_bf16_f32 v71, v34, v35
	global_store_dwordx4 v[82:83], v[56:59], off
	global_store_dwordx4 v[60:61], v[68:71], off

; __device__ __forceinline__ void phase_prep(const Args& a, PG8_LAS unsigned char* lds) {
;     ...
;         const int hp = unit & 1, bn = unit >> 1, h = 2 * hp + half, item = bn * 4 + h; const size_t r0 = (size_t)bn * 64;
;         unsigned char* pi = a.ws + WS_PREP + (size_t)item * PREP_ITEM;
;         bf16_t* wp = (bf16_t*)(pi + PI_W); bf16_t* qgp = (bf16_t*)(pi + PI_QG); bf16_t* kdTp = (bf16_t*)(pi + PI_KD); bf16_t* uT = (bf16_t*)(pi + PI_UT); bf16_t* aqkp = (bf16_t*)(pi + PI_AQ);
;         const bf16_t* qbase = qb + r0 * 512 + h * 128; const bf16_t* kbase = kb + r0 * 512 + h * 128;
;         const bf16_t* kTb = kT + ((size_t)bn * 512 + h * 128) * 64; const bf16_t* vTb = vT + ((size_t)bn * 512 + h * 128) * 64;
;         bf16x8 ak[4], aq[4], bkf[2][4];
; #pragma unroll
;         for (int s = 0; s < 4; ++s) { ak[s] = *(const bf16x8*)(kbase + (size_t)(16 * lw + r) * 512 + 32 * s + 8 * q); aq[s] = *(const bf16x8*)(qbase + (size_t)(16 * lw + r) * 512 + 32 * s + 8 * q); }
; #pragma unroll
;         for (int tj = 0; tj < 2; ++tj)
; #pragma unroll
;             for (int s = 0; s < 4; ++s) bkf[tj][s] = *(const bf16x8*)(kbase + (size_t)(16 * tj + r) * 512 + 32 * s + 8 * q);
;         bf16x8 pv[2][2], pk[2][2];
;         if (role != 0) {
; #pragma unroll
;         for (int cc = 0; cc < 2; ++cc) { const int ct = 2 * lw + cc;
;             pv[cc][0] = *(const bf16x8*)(vTb + (size_t)(16 * ct + r) * 64 + 8 * q); pv[cc][1] = *(const bf16x8*)(vTb + (size_t)(16 * ct + r) * 64 + 32 + 8 * q);
;             pk[cc][0] = *(const bf16x8*)(kTb + (size_t)(16 * ct + r) * 64 + 8 * q); pk[cc][1] = *(const bf16x8*)(kTb + (size_t)(16 * ct + r) * 64 + 32 + 8 * q); } }
;         float gv = gB[(r0 + lane) * 4 + h];
.LBB0_253:
	s_ashr_i32 s18, s38, 1
	s_lshl_b32 s14, s38, 1
	s_and_b32 s14, s14, 2
	s_ashr_i32 s19, s18, 31
	s_add_i32 s26, s14, s33
	s_lshl_b64 s[20:21], s[18:19], 15
	s_lshl_b64 s[24:25], s[18:19], 16
	v_readlane_b32 s14, v253, 43
	s_add_u32 s22, s14, s24
	v_readlane_b32 s14, v253, 44
	s_addc_u32 s23, s14, s25
	s_lshl_b32 s14, s26, 7
	s_lshl_b32 s27, s26, 8
	s_add_u32 s22, s22, s27
	s_addc_u32 s23, s23, 0
	v_readlane_b32 s39, v253, 45
	s_add_u32 s39, s39, s24
	v_readlane_b32 s40, v253, 46
	s_addc_u32 s40, s40, s25
	s_add_u32 vcc_lo, s39, s27
	s_addc_u32 vcc_hi, s40, 0
	s_cmp_eq_u32 s99, 1
	s_cbranch_scc1 .Lpf_skip
	v_mov_b32_e32 v107, v97
	v_lshl_add_u64 v[32:33], vcc, 0, v[106:107]
	v_lshl_add_u64 v[34:35], s[22:23], 0, v[106:107]
	v_lshl_add_u64 v[32:33], v[32:33], 0, v[96:97]
	v_lshl_add_u64 v[36:37], v[34:35], 0, v[96:97]
	s_lshl_b64 s[100:101], s[18:19], 8
	v_mov_b32_e32 v129, s101
	v_or_b32_e32 v128, s100, v98
	s_mov_b32 s100, s26
	s_mov_b32 s101, s15
	v_lshl_add_u64 v[128:129], v[128:129], 0, s[100:101]
	v_lshl_add_u64 v[230:231], v[128:129], 2, s[8:9]
	global_load_dword v234, v[230:231], off
	v_readlane_b32 s100, v253, 49
	v_readlane_b32 s101, v253, 50
	s_nop 1
	v_lshl_add_u64 v[232:233], v[128:129], 2, s[100:101]
	global_load_dword v111, v[232:233], off
	global_load_dwordx4 v[56:59], v[32:33], off
	global_load_dwordx4 v[48:51], v[32:33], off offset:64
	global_load_dwordx4 v[60:63], v[36:37], off
	global_load_dwordx4 v[52:55], v[36:37], off offset:64
	global_load_dwordx4 v[40:43], v[32:33], off offset:128
	s_nop 0
	global_load_dwordx4 v[32:35], v[32:33], off offset:192
	s_nop 0
	global_load_dwordx4 v[44:47], v[36:37], off offset:128
	s_nop 0
	global_load_dwordx4 v[36:39], v[36:37], off offset:192
	v_lshl_add_u64 v[64:65], vcc, 0, v[96:97]
	v_mov_b32_e32 v109, v97
	v_lshl_add_u64 v[126:127], v[64:65], 0, v[108:109]
	s_movk_i32 s22, 0x4000
	v_add_co_u32_e32 v64, vcc, s22, v126
	v_addc_co_u32_e32 v65, vcc, 0, v127, vcc
	s_nop 0
.Lpf_skip:
	s_lshl_b64 s[22:23], s[14:15], 6
	s_add_u32 s20, s22, s20
	s_addc_u32 s21, s23, s21
	s_lshl_b64 s[22:23], s[20:21], 1
	s_add_u32 s20, s10, s22
	s_addc_u32 s21, s11, s23
	v_readlane_b32 s14, v253, 47
	v_readlane_b32 s40, v253, 53
	s_add_u32 s22, s14, s22
	v_readlane_b32 s14, v253, 48
	v_readlane_b32 s41, v253, 54
	s_addc_u32 s23, s14, s23
	s_waitcnt vmcnt(8)
	s_andn2_b64 vcc, exec, s[40:41]
	s_cbranch_vccnz .LBB0_255
	v_mov_b32_e32 v115, v97
	v_lshl_add_u64 v[0:1], s[22:23], 0, v[114:115]
	v_lshl_add_u64 v[8:9], s[20:21], 0, v[114:115]
	v_lshl_add_u64 v[16:17], v[0:1], 0, v[96:97]
	v_lshl_add_u64 v[24:25], v[8:9], 0, v[96:97]
	global_load_dwordx4 v[0:3], v[16:17], off
	global_load_dwordx4 v[4:7], v[16:17], off offset:64
	global_load_dwordx4 v[8:11], v[24:25], off
	global_load_dwordx4 v[12:15], v[24:25], off offset:64
	global_load_dwordx4 v[20:23], v[16:17], off offset:2048
	global_load_dwordx4 v[28:31], v[16:17], off offset:2112
	s_nop 0
	global_load_dwordx4 v[16:19], v[24:25], off offset:2048
	s_nop 0
	global_load_dwordx4 v[24:27], v[24:25], off offset:2112

; __device__ __forceinline__ void phase_prep(const Args& a, PG8_LAS unsigned char* lds) {
;     ...
;         for (int s = 0; s < 4; ++s) { ak[s] = *(const bf16x8*)(kbase + (size_t)(16 * lw + r) * 512 + 32 * s + 8 * q); aq[s] = *(const bf16x8*)(qbase + (size_t)(16 * lw + r) * 512 + 32 * s + 8 * q); }
; #pragma unroll
;         for (int tj = 0; tj < 2; ++tj)
; #pragma unroll
;             for (int s = 0; s < 4; ++s) bkf[tj][s] = *(const bf16x8*)(kbase + (size_t)(16 * tj + r) * 512 + 32 * s + 8 * q);
;         bf16x8 pv[2][2], pk[2][2];
;         if (role != 0) {
; #pragma unroll
;         for (int cc = 0; cc < 2; ++cc) { const int ct = 2 * lw + cc;
;             pv[cc][0] = *(const bf16x8*)(vTb + (size_t)(16 * ct + r) * 64 + 8 * q); pv[cc][1] = *(const bf16x8*)(vTb + (size_t)(16 * ct + r) * 64 + 32 + 8 * q);
;             pk[cc][0] = *(const bf16x8*)(kTb + (size_t)(16 * ct + r) * 64 + 8 * q); pk[cc][1] = *(const bf16x8*)(kTb + (size_t)(16 * ct + r) * 64 + 32 + 8 * q); } }
;         float gv = gB[(r0 + lane) * 4 + h];
.LBB0_259:
	s_or_b64 exec, exec, s[26:27]
	v_readlane_b32 s40, v253, 53
	v_readlane_b32 s41, v253, 54
	s_andn2_b64 vcc, exec, s[40:41]
	s_cmp_eq_u32 s99, 1
	s_cbranch_scc1 .Lpf_w
	s_cbranch_vccnz .Lpp_w0
	s_waitcnt vmcnt(8)
	s_branch .Lpp_w1
.Lpp_w0:
	s_waitcnt vmcnt(0)
	s_branch .Lpp_w1
.Lpf_w:
	s_cbranch_vccnz .Lpf_w0
	s_waitcnt vmcnt(20)
	s_branch .Lpf_mv
.Lpf_w0:
	s_waitcnt vmcnt(6)
.Lpf_mv:
	v_mov_b64_e32 v[56:57], v[84:85]
	v_mov_b64_e32 v[58:59], v[86:87]
	v_mov_b64_e32 v[48:49], v[88:89]
	v_mov_b64_e32 v[50:51], v[90:91]
	v_mov_b64_e32 v[40:41], v[92:93]
	v_mov_b64_e32 v[42:43], v[94:95]
	v_mov_b64_e32 v[32:33], v[236:237]
	v_mov_b64_e32 v[34:35], v[238:239]
	v_mov_b64_e32 v[60:61], v[240:241]
	v_mov_b64_e32 v[62:63], v[242:243]
	v_mov_b64_e32 v[52:53], v[244:245]
	v_mov_b64_e32 v[54:55], v[246:247]
	v_mov_b64_e32 v[44:45], v[248:249]
	v_mov_b64_e32 v[46:47], v[250:251]
	v_mov_b64_e32 v[36:37], v[126:127]
	v_mov_b64_e32 v[38:39], v[128:129]
